# additionally: rw_mix issues its 4 row loads together and hoists parameter loads; rwkv_post stages the As tile with one wait and issues next-group parameter loads ahead of the output store
# speedup vs baseline: 1.0264x; 1.0054x over previous
; #define LAS __attribute__((address_space(3)))
; #define IN(k) ((const float*)kload(8 * (k)))
; #define WSP() ((unsigned char*)kload(280))
; DI int tid_opaque() { int t = threadIdx.x; asm volatile("" : "+v"(t)); return t; }
; DI void rwkv_post_tile(int j, int item, LAS unsigned char* lds) {
;     const int tile = item >> 2, ncq = item & 3;
;     unsigned char* ws = WSP();
;     const int tid = tid_opaque(), wave = __builtin_amdgcn_readfirstlane(tid >> 6), lane = tid & 63, fr = lane & 15, fq = lane >> 4;
;     LAS bf16_t* As = (LAS bf16_t*)lds; LAS bf16_t* Bs = As + 128 * 200;
;     const bf16_t* G1 = (const bf16_t*)(ws + OD_G1); const bf16_t* G2 = (const bf16_t*)(ws + W_G2_T) + (size_t)j * D * 192;
;     const bf16_t* Y0 = (const bf16_t*)(ws + OD_Y); const bf16_t* Y1 = Y0 + (size_t)M * D;
;     const bf16_t* Vb = (const bf16_t*)(ws + OD_RKV) + (size_t)2 * M * D; bf16_t* Yo = (bf16_t*)(ws + OD_RKV);
;     const float* SB0 = (const float*)(ws + OD_SB); const float* SB1 = SB0 + (size_t)M * 16;
;     const float* lng = IN(31) + j * D; const float* lnb = IN(32) + j * D;
;     const int m0 = tile * 128;
;     __syncthreads();
;     for (int i = 0; i < 6; ++i) { const int idx = tid + 512 * i; const int row = idx / 24, ch = idx - row * 24;
;         *(LAS u32x4*)(As + row * 200 + ch * 8) = *(const u32x4*)(G1 + (size_t)(m0 + row) * 256 + ch * 8); }
;     const size_t m = (size_t)m0 + wave * 16 + fr;
;     for (int nc = ncq * 2; nc < ncq * 2 + 2; ++nc) {
;         __syncthreads();
;         for (int i = 0; i < 6; ++i) { const int idx = tid + 512 * i; const int row = idx / 24, ch = idx - row * 24;
;             *(LAS u32x4*)(Bs + row * 200 + ch * 8) = *(const u32x4*)(G2 + (size_t)(nc * 128 + row) * 192 + ch * 8); }
.LBB0_98:
	s_andn2_b64 vcc, exec, s[2:3]
	s_cbranch_vccnz .LBB0_95
	v_readlane_b32 s14, v255, 17
	v_readlane_b32 s15, v255, 18
	s_mov_b64 s[4:5], s[14:15]
	s_waitcnt lgkmcnt(0)
	s_load_dwordx2 s[12:13], s[4:5], 0x118
	s_bfe_u32 s3, s18, 0x20001
	s_and_b32 s24, s20, 0xffffff80
	s_lshl_b32 s2, s3, 8
	s_ashr_i32 s25, s24, 31
	v_mov_b32_e32 v0, v182
	s_mov_b32 s26, 0x2aaaaaab
	s_waitcnt lgkmcnt(0)
	s_add_u32 s16, s12, 0x1d500000
	s_waitcnt vmcnt(0)
	v_mul_hi_i32 v2, v0, s26
	s_addc_u32 s17, s13, 0
	s_lshl_b32 s29, s23, 5
	v_lshrrev_b32_e32 v3, 31, v2
	v_ashrrev_i32_e32 v2, 2, v2
	s_and_b32 s29, s29, 0xffffff80
	v_add_u32_e32 v20, v2, v3
	v_add_u32_e32 v2, s29, v20
	s_movk_i32 s27, 0xffe8
	v_ashrrev_i32_e32 v3, 31, v2
	v_mad_u64_u32 v[8:9], s[34:35], v20, s27, v[0:1]
	v_lshlrev_b64 v[2:3], 9, v[2:3]
	v_lshl_add_u64 v[4:5], s[16:17], 0, v[2:3]
	v_lshlrev_b32_e32 v2, 3, v8
	s_mov_b64 s[4:5], s[14:15]
	v_ashrrev_i32_e32 v3, 31, v2
	v_lshlrev_b64 v[2:3], 1, v[2:3]
	s_load_dwordx2 s[4:5], s[4:5], 0xf8
	v_lshl_add_u64 v[4:5], v[4:5], 0, v[2:3]
	s_load_dwordx2 s[14:15], s[14:15], 0x100
	s_waitcnt vmcnt(0) lgkmcnt(0)
	s_barrier
	global_load_dwordx4 v[240:243], v[4:5], off
	s_movk_i32 s36, 0x190
	v_mul_lo_u32 v9, v20, s36
	v_lshl_add_u32 v21, v8, 4, v9
	v_readfirstlane_b32 s28, v0
	v_add_u32_e32 v167, 0xc810, v21
	v_add_u32_e32 v4, 0x200, v0
	v_mul_hi_i32 v5, v4, s26
	v_lshrrev_b32_e32 v6, 31, v5
	v_ashrrev_i32_e32 v5, 2, v5
	v_add_u32_e32 v22, v5, v6
	v_mad_u64_u32 v[10:11], s[34:35], v22, s27, v[4:5]
	v_add_u32_e32 v4, s29, v22
	v_ashrrev_i32_e32 v5, 31, v4
	v_lshlrev_b64 v[4:5], 9, v[4:5]
	v_lshl_add_u64 v[6:7], s[16:17], 0, v[4:5]
	v_lshlrev_b32_e32 v4, 3, v10
	v_ashrrev_i32_e32 v5, 31, v4
	v_lshlrev_b64 v[4:5], 1, v[4:5]
	v_lshl_add_u64 v[6:7], v[6:7], 0, v[4:5]
	global_load_dwordx4 v[218:221], v[6:7], off
	v_mul_lo_u32 v11, v22, s36
	v_lshl_add_u32 v23, v10, 4, v11
	v_add_u32_e32 v168, 0xc810, v23
	v_add_u32_e32 v6, 0x400, v0
	v_mul_hi_i32 v7, v6, s26
	v_lshrrev_b32_e32 v8, 31, v7
	v_ashrrev_i32_e32 v7, 2, v7
	v_add_u32_e32 v24, v7, v8
	v_mad_u64_u32 v[10:11], s[34:35], v24, s27, v[6:7]
	v_add_u32_e32 v6, s29, v24
	v_ashrrev_i32_e32 v7, 31, v6
	v_lshlrev_b32_e32 v8, 3, v10
	v_lshlrev_b64 v[6:7], 9, v[6:7]
	v_ashrrev_i32_e32 v9, 31, v8
	v_lshl_add_u64 v[6:7], s[16:17], 0, v[6:7]
	v_lshlrev_b64 v[12:13], 1, v[8:9]
	v_lshl_add_u64 v[6:7], v[6:7], 0, v[12:13]
	global_load_dwordx4 v[222:225], v[6:7], off
	v_mul_lo_u32 v11, v24, s36
	v_lshl_add_u32 v25, v10, 4, v11
	v_add_u32_e32 v169, 0xc810, v25
	v_add_u32_e32 v6, 0x600, v0
	v_mul_hi_i32 v7, v6, s26
	v_lshrrev_b32_e32 v8, 31, v7
	v_ashrrev_i32_e32 v7, 2, v7
	v_add_u32_e32 v26, v7, v8
	v_mad_u64_u32 v[10:11], s[34:35], v26, s27, v[6:7]
	v_add_u32_e32 v6, s29, v26
	v_ashrrev_i32_e32 v7, 31, v6
	v_lshlrev_b32_e32 v8, 3, v10
	v_lshlrev_b64 v[6:7], 9, v[6:7]
	v_ashrrev_i32_e32 v9, 31, v8
	v_lshl_add_u64 v[6:7], s[16:17], 0, v[6:7]
	v_lshlrev_b64 v[14:15], 1, v[8:9]
	v_lshl_add_u64 v[6:7], v[6:7], 0, v[14:15]
	global_load_dwordx4 v[226:229], v[6:7], off
	v_mul_lo_u32 v11, v26, s36
	v_lshl_add_u32 v27, v10, 4, v11
	v_add_u32_e32 v170, 0xc810, v27
	v_add_u32_e32 v6, 0x800, v0
	v_mul_hi_i32 v7, v6, s26
	v_lshrrev_b32_e32 v8, 31, v7
	v_ashrrev_i32_e32 v7, 2, v7
	v_add_u32_e32 v28, v7, v8
	v_mad_u64_u32 v[10:11], s[34:35], v28, s27, v[6:7]
	v_add_u32_e32 v6, s29, v28
	v_ashrrev_i32_e32 v7, 31, v6
	v_lshlrev_b32_e32 v8, 3, v10
	v_lshlrev_b64 v[6:7], 9, v[6:7]
	v_ashrrev_i32_e32 v9, 31, v8
	v_lshl_add_u64 v[6:7], s[16:17], 0, v[6:7]
	v_lshlrev_b64 v[16:17], 1, v[8:9]
	v_lshl_add_u64 v[6:7], v[6:7], 0, v[16:17]
	global_load_dwordx4 v[230:233], v[6:7], off
	v_mul_lo_u32 v11, v28, s36
	v_lshl_add_u32 v29, v10, 4, v11
	v_add_u32_e32 v171, 0xc810, v29
	v_add_u32_e32 v6, 0xa00, v0
	v_mul_hi_i32 v7, v6, s26
	v_lshrrev_b32_e32 v8, 31, v7
	v_ashrrev_i32_e32 v7, 2, v7
	v_add_u32_e32 v30, v7, v8
	v_mad_u64_u32 v[10:11], s[34:35], v30, s27, v[6:7]
	v_add_u32_e32 v6, s29, v30
	v_ashrrev_i32_e32 v7, 31, v6
	v_lshlrev_b32_e32 v8, 3, v10
	v_lshlrev_b64 v[6:7], 9, v[6:7]
	v_ashrrev_i32_e32 v9, 31, v8
	v_lshl_add_u64 v[6:7], s[16:17], 0, v[6:7]
	v_lshlrev_b64 v[18:19], 1, v[8:9]
	v_lshl_add_u64 v[6:7], v[6:7], 0, v[18:19]
	global_load_dwordx4 v[236:239], v[6:7], off
	s_ashr_i32 s16, s28, 2
	v_mul_lo_u32 v11, v30, s36
	s_and_b32 s28, s16, -16
	v_lshl_add_u32 v10, v10, 4, v11
	s_mul_i32 s16, s28, 0x190
	v_and_b32_e32 v11, 15, v0
	v_bfe_u32 v0, v0, 4, 2
	s_movk_i32 s26, 0x180
	s_ashr_i32 s29, s28, 31
	v_mul_u32_u24_e32 v31, 0x190, v11
	v_add_u32_e32 v172, 0xc810, v10
	s_waitcnt vmcnt(0)
	ds_write_b128 v21, v[240:243] offset:16
	ds_write_b128 v23, v[218:221] offset:16
	ds_write_b128 v25, v[222:225] offset:16
	ds_write_b128 v27, v[226:229] offset:16
	ds_write_b128 v29, v[230:233] offset:16
	ds_write_b128 v10, v[236:239] offset:16
	v_mov_b32_e32 v6, s16
	v_mad_u32_u24 v6, v11, s36, v6
	v_lshlrev_b32_e32 v7, 4, v0
	v_add3_u32 v139, v6, v7, 16
	v_add_u32_e32 v32, 0xc810, v7
	v_and_b32_e32 v7, 64, v187
	v_xor_b32_e32 v6, 16, v187
	v_add_u32_e32 v7, 64, v7
	v_cmp_lt_i32_e32 vcc, v6, v7
	v_add_u32_e32 v8, s2, v20
	v_lshl_or_b32 v0, v0, 2, s2
	v_cndmask_b32_e32 v6, v187, v6, vcc
	v_lshlrev_b32_e32 v165, 2, v6
	v_xor_b32_e32 v6, 32, v187
	v_cmp_lt_i32_e32 vcc, v6, v7
	v_add_u32_e32 v173, v32, v31
	s_nop 0
	v_cndmask_b32_e32 v6, v187, v6, vcc
	v_lshlrev_b32_e32 v166, 2, v6
	v_mov_b64_e32 v[6:7], s[80:81]
	v_mad_i64_i32 v[8:9], s[16:17], v8, s26, v[6:7]
	s_add_u32 s16, s24, s28
	s_addc_u32 s17, s25, s29
	v_lshl_add_u64 v[70:71], v[8:9], 0, v[2:3]
	v_or_b32_e32 v2, s16, v11
	v_mov_b32_e32 v3, s17
	v_add_u32_e32 v8, s2, v22
	v_lshlrev_b64 v[72:73], 6, v[2:3]
	v_mad_i64_i32 v[8:9], s[16:17], v8, s26, v[6:7]
	v_lshlrev_b64 v[80:81], 11, v[2:3]
	v_add_u32_e32 v2, s2, v28
	v_lshl_add_u64 v[74:75], v[8:9], 0, v[4:5]
	v_add_u32_e32 v4, s2, v24
	v_mad_i64_i32 v[2:3], s[16:17], v2, s26, v[6:7]
	v_mad_i64_i32 v[4:5], s[16:17], v4, s26, v[6:7]
	v_lshl_add_u64 v[82:83], v[2:3], 0, v[16:17]
	v_add_u32_e32 v2, s2, v30
	v_lshl_or_b32 v72, s3, 4, v72
	v_lshl_add_u64 v[76:77], v[4:5], 0, v[12:13]
	v_add_u32_e32 v4, s2, v26
	v_mad_i64_i32 v[2:3], s[2:3], v2, s26, v[6:7]
	s_add_u32 s2, s14, s22
	v_lshl_or_b32 v80, v0, 1, v80
	s_addc_u32 s3, s15, 0
	v_lshlrev_b32_e32 v0, 2, v0
	v_lshl_add_u64 v[86:87], s[2:3], 0, v[0:1]
	s_add_u32 s2, s4, s22
	v_mad_i64_i32 v[4:5], s[16:17], v4, s26, v[6:7]
	s_addc_u32 s3, s5, 0
	v_lshl_add_u64 v[78:79], v[4:5], 0, v[14:15]
	v_lshl_add_u64 v[84:85], v[2:3], 0, v[18:19]
	v_lshl_add_u64 v[88:89], s[2:3], 0, v[0:1]
	s_mov_b64 s[14:15], 0
	s_mov_b32 s3, 0x800000
	s_mov_b64 s[16:17], 0x100
	s_mov_b64 s[24:25], 0xc000
; #define LAS __attribute__((address_space(3)))
; DI void rwkv_post_tile(int j, int item, LAS unsigned char* lds) {
;     ...
;     for (int nc = ncq * 2; nc < ncq * 2 + 2; ++nc) {
;         __syncthreads();
;         for (int i = 0; i < 6; ++i) { const int idx = tid + 512 * i; const int row = idx / 24, ch = idx - row * 24;
;             *(LAS u32x4*)(Bs + row * 200 + ch * 8) = *(const u32x4*)(G2 + (size_t)(nc * 128 + row) * 192 + ch * 8); }
;         __syncthreads();
;         f32x4 acc[8];
; #pragma unroll
;         for (int i = 0; i < 8; ++i) acc[i] = (f32x4){0.f, 0.f, 0.f, 0.f};
;         mm16<8, 6>(As + wave * 16 * 200, 200, Bs, 200, acc, fr, fq);
.LBB0_100:
	v_lshl_add_u64 v[2:3], s[12:13], 0, v[70:71]
	v_lshl_add_u64 v[6:7], s[12:13], 0, v[74:75]
	v_lshl_add_u64 v[10:11], s[12:13], 0, v[76:77]
	v_lshl_add_u64 v[14:15], s[12:13], 0, v[78:79]
	v_lshl_add_u64 v[18:19], s[12:13], 0, v[82:83]
	v_lshl_add_u64 v[22:23], s[12:13], 0, v[84:85]
	s_waitcnt lgkmcnt(0)
	s_barrier
	global_load_dwordx4 v[2:5], v[2:3], off
	s_nop 0
	global_load_dwordx4 v[6:9], v[6:7], off
	s_nop 0
	global_load_dwordx4 v[10:13], v[10:11], off
	s_nop 0
	global_load_dwordx4 v[14:17], v[14:15], off
	s_nop 0
	global_load_dwordx4 v[18:21], v[18:19], off
	s_nop 0
	global_load_dwordx4 v[22:25], v[22:23], off
	s_mov_b32 s2, 0x7000000
	v_lshl_add_u64 v[68:69], s[12:13], 0, v[72:73]
	v_lshl_add_u64 v[94:95], v[88:89], 0, s[14:15]
	v_lshl_add_u64 v[96:97], v[86:87], 0, s[14:15]
	v_mov_b32_e32 v116, v1
	v_mov_b32_e32 v118, v1
	v_mov_b32_e32 v164, 0x3a27c5ac
	s_mov_b32 s4, 0x3c800000
	s_add_u32 s14, s14, 0x200
	s_addc_u32 s15, s15, 0
	v_lshl_add_u64 v[70:71], v[70:71], 0, s[24:25]
	v_lshl_add_u64 v[72:73], v[72:73], 0, 8
	v_lshl_add_u64 v[74:75], v[74:75], 0, s[24:25]
	v_lshl_add_u64 v[76:77], v[76:77], 0, s[24:25]
	v_lshl_add_u64 v[78:79], v[78:79], 0, s[24:25]
	v_lshl_add_u64 v[82:83], v[82:83], 0, s[24:25]
	v_lshl_add_u64 v[84:85], v[84:85], 0, s[24:25]
	s_cmpk_lg_i32 s14, 0x400
	s_waitcnt vmcnt(5)
	ds_write_b128 v167, v[2:5]
	s_waitcnt vmcnt(4)
	ds_write_b128 v168, v[6:9]
	s_waitcnt vmcnt(3)
	ds_write_b128 v169, v[10:13]
	s_waitcnt vmcnt(2)
	ds_write_b128 v170, v[14:17]
	s_waitcnt vmcnt(1)
	ds_write_b128 v171, v[18:21]
	s_waitcnt vmcnt(0)
	ds_write_b128 v172, v[22:25]
	s_waitcnt lgkmcnt(0)
	s_barrier
	ds_read_b128 v[2:5], v173
	ds_read_b128 v[10:13], v139
	ds_read_b128 v[6:9], v139 offset:64
	ds_read_b128 v[22:25], v173 offset:64
	ds_read_b128 v[14:17], v173 offset:6400
	ds_read_b128 v[58:61], v173 offset:6464
	s_waitcnt lgkmcnt(1)
	v_mfma_f32_16x16x32_bf16 v[62:65], v[14:17], v[10:13], 0
	ds_read_b128 v[14:17], v173 offset:12800
	ds_read_b128 v[50:53], v173 offset:12864
	s_waitcnt lgkmcnt(1)
	v_mfma_f32_16x16x32_bf16 v[54:57], v[14:17], v[10:13], 0
	ds_read_b128 v[14:17], v173 offset:19200
	ds_read_b128 v[42:45], v173 offset:19264
	s_waitcnt lgkmcnt(1)
	v_mfma_f32_16x16x32_bf16 v[46:49], v[14:17], v[10:13], 0
	ds_read_b128 v[14:17], v173 offset:25600
	ds_read_b128 v[34:37], v173 offset:25664
	s_waitcnt lgkmcnt(1)
	v_mfma_f32_16x16x32_bf16 v[38:41], v[14:17], v[10:13], 0
	ds_read_b128 v[18:21], v173 offset:32000
	ds_read_b128 v[14:17], v173 offset:32064
	ds_read_b128 v[30:33], v173 offset:38400
	ds_read_b128 v[26:29], v173 offset:38464
	v_mfma_f32_16x16x32_bf16 v[42:45], v[42:45], v[6:9], v[46:49]
	s_nop 2
	ds_read_b128 v[46:49], v173 offset:128
	v_mfma_f32_16x16x32_bf16 v[2:5], v[2:5], v[10:13], 0
	s_waitcnt lgkmcnt(4)
	v_mfma_f32_16x16x32_bf16 v[18:21], v[18:21], v[10:13], 0
	s_waitcnt lgkmcnt(2)
	v_mfma_f32_16x16x32_bf16 v[30:33], v[30:33], v[10:13], 0
	v_mfma_f32_16x16x32_bf16 v[22:25], v[22:25], v[6:9], v[2:5]
	v_mfma_f32_16x16x32_bf16 v[34:37], v[34:37], v[6:9], v[38:41]
	v_mfma_f32_16x16x32_bf16 v[38:41], v[14:17], v[6:9], v[18:21]
	s_waitcnt lgkmcnt(1)
	v_mfma_f32_16x16x32_bf16 v[26:29], v[26:29], v[6:9], v[30:33]
	s_nop 0
	ds_read_b128 v[18:21], v139 offset:128
	ds_read_b128 v[14:17], v139 offset:192
	ds_read_b128 v[30:33], v173 offset:192
	v_mfma_f32_16x16x32_bf16 v[2:5], v[58:61], v[6:9], v[62:65]
	v_lshl_add_u64 v[58:59], s[12:13], 0, v[80:81]
	v_add_co_u32_e32 v92, vcc, s2, v58
	v_mfma_f32_16x16x32_bf16 v[50:53], v[50:53], v[6:9], v[54:57]
	s_nop 0
	v_addc_co_u32_e32 v93, vcc, 0, v59, vcc
	s_mov_b32 s2, 0xb400000
	s_waitcnt lgkmcnt(2)
	v_mfma_f32_16x16x32_bf16 v[22:25], v[46:49], v[18:21], v[22:25]
	ds_read_b128 v[46:49], v173 offset:6528
	ds_read_b128 v[54:57], v173 offset:6592
	v_add_co_u32_e32 v98, vcc, s2, v58
	s_waitcnt lgkmcnt(1)
	v_mfma_f32_16x16x32_bf16 v[2:5], v[46:49], v[18:21], v[2:5]
	ds_read_b128 v[46:49], v173 offset:12928
	ds_read_b128 v[60:63], v173 offset:12992
	v_addc_co_u32_e32 v99, vcc, 0, v59, vcc
	s_waitcnt lgkmcnt(1)
	v_mfma_f32_16x16x32_bf16 v[46:49], v[46:49], v[18:21], v[50:53]
	s_nop 2
	ds_read_b128 v[50:53], v173 offset:19328
	ds_read_b128 v[64:67], v173 offset:19392
	s_mov_b32 s2, 0x1e600000
	v_add_co_u32_e32 v100, vcc, s2, v68
	s_waitcnt lgkmcnt(1)
	v_mfma_f32_16x16x32_bf16 v[42:45], v[50:53], v[18:21], v[42:45]
	ds_read_b128 v[50:53], v173 offset:25728
	ds_read_b128 v[104:107], v173 offset:25792
	v_addc_co_u32_e32 v101, vcc, 0, v69, vcc
	s_waitcnt lgkmcnt(1)
	v_mfma_f32_16x16x32_bf16 v[34:37], v[50:53], v[18:21], v[34:37]
	ds_read_b128 v[50:53], v173 offset:32128
	ds_read_b128 v[108:111], v173 offset:32192
	s_mov_b32 s2, 0x1e820000
	v_add_co_u32_e32 v102, vcc, s2, v68
	s_waitcnt lgkmcnt(1)
	v_mfma_f32_16x16x32_bf16 v[38:41], v[50:53], v[18:21], v[38:41]
	ds_read_b128 v[50:53], v173 offset:38528
	ds_read_b128 v[112:115], v173 offset:38592
	v_addc_co_u32_e32 v103, vcc, 0, v69, vcc
	s_brev_b32 s2, 24
	v_add_co_u32_e32 v136, vcc, s2, v58
	s_mov_b32 s2, 0xf800000
	s_nop 0
	v_addc_co_u32_e32 v137, vcc, 0, v59, vcc
	v_mfma_f32_16x16x32_bf16 v[30:33], v[30:33], v[14:17], v[22:25]
	v_add_co_u32_e32 v90, vcc, s2, v58
	global_load_dwordx2 v[144:145], v[92:93], off
	global_load_dwordx2 v[146:147], v[98:99], off
	ds_read_b128 v[22:25], v139 offset:256
	s_waitcnt lgkmcnt(2)
; DI void rwkv_post_tile(int j, int item, LAS unsigned char* lds) {
;     ...
;         mm16<8, 6>(As + wave * 16 * 200, 200, Bs, 200, acc, fr, fq);
; #pragma unroll
;         for (int hh = 0; hh < 2; ++hh) {
;             const int H = nc * 2 + hh; float y[4][4]; float sum = 0.f;
; #pragma unroll
;             for (int q = 0; q < 4; ++q) { const int c = nc * 128 + (hh * 4 + q) * 16 + fq * 4;
;                 const u32x2 a = *(const u32x2*)(Y0 + m * D + c), bq = *(const u32x2*)(Y1 + m * D + c);
;                 y[q][0] = bflo(a.x) + bflo(bq.x); y[q][1] = bfhi(a.x) + bfhi(bq.x); y[q][2] = bflo(a.y) + bflo(bq.y); y[q][3] = bfhi(a.y) + bfhi(bq.y);
;                 sum += y[q][0] + y[q][1] + y[q][2] + y[q][3]; }
;             sum += __shfl_xor(sum, 16); sum += __shfl_xor(sum, 32);
	v_mfma_f32_16x16x32_bf16 v[26:29], v[50:53], v[18:21], v[26:29]
	v_addc_co_u32_e32 v91, vcc, 0, v59, vcc
	v_lshl_add_u64 v[80:81], v[80:81], 0, s[16:17]
	v_mfma_f32_16x16x32_bf16 v[50:53], v[54:57], v[14:17], v[2:5]
	v_mfma_f32_16x16x32_bf16 v[46:49], v[60:63], v[14:17], v[46:49]
	ds_read_b128 v[54:57], v173 offset:256
	ds_read_b128 v[58:61], v173 offset:6656
	global_load_dwordx2 v[148:149], v[98:99], off offset:32
	global_load_dwordx2 v[150:151], v[92:93], off offset:32
	v_mfma_f32_16x16x32_bf16 v[42:45], v[64:67], v[14:17], v[42:45]
	ds_read_b128 v[62:65], v173 offset:13056
	ds_read_b128 v[66:69], v173 offset:19456
	s_waitcnt vmcnt(1)
	v_and_b32_e32 v199, 0xffff0000, v148
	v_mfma_f32_16x16x32_bf16 v[34:37], v[104:107], v[14:17], v[34:37]
	v_mfma_f32_16x16x32_bf16 v[38:41], v[108:111], v[14:17], v[38:41]
	ds_read_b128 v[2:5], v139 offset:320
	ds_read_b128 v[108:111], v173 offset:320
	global_load_dwordx2 v[152:153], v[92:93], off offset:64
	global_load_dwordx2 v[154:155], v[98:99], off offset:64
	s_waitcnt lgkmcnt(7)
	v_mfma_f32_16x16x32_bf16 v[104:107], v[112:115], v[14:17], v[26:29]
	ds_read_b128 v[112:115], v173 offset:6720
	s_waitcnt vmcnt(1)
	v_lshlrev_b32_e32 v202, 16, v153
	s_waitcnt lgkmcnt(6)
	v_mfma_f32_16x16x32_bf16 v[54:57], v[54:57], v[22:25], v[30:33]
	ds_read_b128 v[26:29], v173 offset:25856
	s_nop 1
	ds_read_b128 v[30:33], v173 offset:32256
	ds_read_b128 v[120:123], v173 offset:13120
	ds_read_b128 v[124:127], v173 offset:38656
	ds_read_b128 v[128:131], v173 offset:19520
	global_load_dwordx2 v[156:157], v[92:93], off offset:96
	global_load_dwordx2 v[158:159], v[98:99], off offset:96
	ds_read_b128 v[132:135], v173 offset:25920
	global_load_dword v0, v[100:101], off
	global_load_dword v117, v[102:103], off
	global_load_dwordx2 v[160:161], v[136:137], off
	s_waitcnt lgkmcnt(11)
	v_mfma_f32_16x16x32_bf16 v[50:53], v[58:61], v[22:25], v[50:53]
	global_load_dwordx4 v[58:61], v[94:95], off
	s_waitcnt vmcnt(6)
	v_lshlrev_b32_e32 v200, 16, v154
	v_and_b32_e32 v201, 0xffff0000, v154
	s_waitcnt lgkmcnt(10)
	v_mfma_f32_16x16x32_bf16 v[46:49], v[62:65], v[22:25], v[46:49]
	global_load_dwordx4 v[62:65], v[96:97], off
	v_and_b32_e32 v154, 0xffff0000, v153
	v_lshlrev_b32_e32 v203, 16, v155
	s_waitcnt lgkmcnt(5)
	v_mfma_f32_16x16x32_bf16 v[140:143], v[26:29], v[22:25], v[34:37]
	ds_read_b128 v[26:29], v173 offset:38720
	v_and_b32_e32 v155, 0xffff0000, v155
	s_waitcnt vmcnt(6)
	v_lshlrev_b32_e32 v153, 16, v157
	ds_read_b128 v[34:37], v173 offset:32320
	s_waitcnt lgkmcnt(6)
	v_mfma_f32_16x16x32_bf16 v[38:41], v[30:33], v[22:25], v[38:41]
	s_waitcnt vmcnt(5)
	v_and_b32_e32 v204, 0xffff0000, v159
	v_lshlrev_b32_e32 v205, 16, v159
	v_and_b32_e32 v206, 0xffff0000, v156
	s_waitcnt lgkmcnt(4)
	v_mfma_f32_16x16x32_bf16 v[30:33], v[124:127], v[22:25], v[104:107]
	global_load_dwordx2 v[124:125], v[136:137], off offset:32
	global_load_dwordx2 v[126:127], v[136:137], off offset:64
	global_load_dwordx2 v[162:163], v[136:137], off offset:96
	global_load_dwordx2 v[174:175], v[92:93], off offset:128
	global_load_dwordx2 v[176:177], v[98:99], off offset:128
	global_load_dwordx2 v[178:179], v[98:99], off offset:160
	global_load_dwordx2 v[180:181], v[92:93], off offset:160
	global_load_dwordx2 v[188:189], v[92:93], off offset:192
	global_load_dwordx2 v[190:191], v[92:93], off offset:224
	global_load_dwordx2 v[192:193], v[98:99], off offset:192
	global_load_dwordx2 v[194:195], v[98:99], off offset:224
	global_load_dwordx2 v[106:107], v[136:137], off offset:128
	v_mfma_f32_16x16x32_bf16 v[42:45], v[66:69], v[22:25], v[42:45]
	global_load_dwordx2 v[98:99], v[136:137], off offset:192
	global_load_dwordx2 v[104:105], v[136:137], off offset:160
	global_load_dwordx2 v[92:93], v[136:137], off offset:224
	v_and_b32_e32 v137, 0xffff0000, v145
	v_and_b32_e32 v136, 0xffff0000, v144
	v_mfma_f32_16x16x32_bf16 v[66:69], v[108:111], v[2:5], v[54:57]
	v_lshlrev_b32_e32 v207, 16, v156
	v_and_b32_e32 v156, 0xffff0000, v158
	s_waitcnt vmcnt(18)
	v_add_f32_e32 v0, v0, v117
	v_mfma_f32_16x16x32_bf16 v[54:57], v[112:115], v[2:5], v[50:53]
	s_waitcnt vmcnt(13)
	v_lshlrev_b32_e32 v113, 16, v127
	v_mfma_f32_16x16x32_bf16 v[50:53], v[120:123], v[2:5], v[46:49]
	v_mov_b32_e32 v110, v66
	v_mov_b32_e32 v111, v68
	v_mov_b32_e32 v68, v67
	s_waitcnt lgkmcnt(3)
	v_mfma_f32_16x16x32_bf16 v[46:49], v[128:131], v[2:5], v[42:45]
	v_mov_b32_e32 v108, v54
	v_mov_b32_e32 v109, v56
	v_mov_b32_e32 v56, v55
	s_waitcnt lgkmcnt(2)
	v_mfma_f32_16x16x32_bf16 v[42:45], v[132:135], v[2:5], v[140:143]
	v_mov_b32_e32 v66, v50
	v_mov_b32_e32 v67, v52
	v_mov_b32_e32 v52, v51
	v_mov_b32_e32 v54, v46
	v_mov_b32_e32 v55, v48
	v_mov_b32_e32 v48, v47
	s_nop 1
	v_mov_b32_e32 v50, v42
	v_mov_b32_e32 v51, v44
	v_mov_b32_e32 v44, v43
	v_lshlrev_b32_e32 v43, 16, v145
	v_lshlrev_b32_e32 v42, 16, v144
	v_lshlrev_b32_e32 v47, 16, v147
	v_lshlrev_b32_e32 v46, 16, v146
	v_and_b32_e32 v141, 0xffff0000, v147
	v_and_b32_e32 v140, 0xffff0000, v146
	v_lshlrev_b32_e32 v142, 16, v148
	v_lshlrev_b32_e32 v144, 16, v150
	v_and_b32_e32 v147, 0xffff0000, v150
	v_lshlrev_b32_e32 v145, 16, v151
	v_and_b32_e32 v148, 0xffff0000, v151
	v_lshlrev_b32_e32 v150, 16, v152
	v_and_b32_e32 v151, 0xffff0000, v152
	v_and_b32_e32 v152, 0xffff0000, v157
	v_lshlrev_b32_e32 v157, 16, v158
	v_lshlrev_b32_e32 v129, 16, v161
	v_lshlrev_b32_e32 v128, 16, v160
	v_and_b32_e32 v131, 0xffff0000, v161
	v_and_b32_e32 v130, 0xffff0000, v160
	v_lshlrev_b32_e32 v121, 16, v125
	v_lshlrev_b32_e32 v120, 16, v124
	v_and_b32_e32 v123, 0xffff0000, v125
	v_and_b32_e32 v122, 0xffff0000, v124
	v_lshlrev_b32_e32 v112, 16, v126
	v_and_b32_e32 v115, 0xffff0000, v127
	v_and_b32_e32 v114, 0xffff0000, v126
	s_waitcnt vmcnt(11)
; DI void rwkv_post_tile(int j, int item, LAS unsigned char* lds) {
;     ...
;             const int H = nc * 2 + hh; float y[4][4]; float sum = 0.f;
; #pragma unroll
;             for (int q = 0; q < 4; ++q) { const int c = nc * 128 + (hh * 4 + q) * 16 + fq * 4;
;                 const u32x2 a = *(const u32x2*)(Y0 + m * D + c), bq = *(const u32x2*)(Y1 + m * D + c);
;                 y[q][0] = bflo(a.x) + bflo(bq.x); y[q][1] = bfhi(a.x) + bfhi(bq.x); y[q][2] = bflo(a.y) + bflo(bq.y); y[q][3] = bfhi(a.y) + bfhi(bq.y);
;                 sum += y[q][0] + y[q][1] + y[q][2] + y[q][3]; }
;             sum += __shfl_xor(sum, 16); sum += __shfl_xor(sum, 32);
;             const float mean = sum * (1.f / 64.f); float vs = 0.f;
; #pragma unroll
;             for (int q = 0; q < 4; ++q)
; #pragma unroll
;                 for (int e = 0; e < 4; ++e) { y[q][e] -= mean; vs += y[q][e] * y[q][e]; }
;             vs += __shfl_xor(vs, 16); vs += __shfl_xor(vs, 32);
	v_lshlrev_b32_e32 v125, 16, v175
	v_lshlrev_b32_e32 v124, 16, v174
	s_waitcnt vmcnt(10)
	v_lshlrev_b32_e32 v127, 16, v177
	v_lshlrev_b32_e32 v126, 16, v176
	v_and_b32_e32 v159, 0xffff0000, v175
	v_and_b32_e32 v158, 0xffff0000, v174
	v_and_b32_e32 v161, 0xffff0000, v177
	v_and_b32_e32 v160, 0xffff0000, v176
	v_lshlrev_b32_e32 v143, 16, v149
	v_and_b32_e32 v149, 0xffff0000, v149
	v_mov_b32_e32 v132, v58
	v_mov_b32_e32 v133, v60
	v_mov_b32_e32 v134, v62
	v_mov_b32_e32 v135, v64
	v_mov_b32_e32 v60, v59
	v_mov_b32_e32 v64, v63
	v_lshlrev_b32_e32 v59, 16, v163
	v_lshlrev_b32_e32 v58, 16, v162
	v_and_b32_e32 v63, 0xffff0000, v163
	v_and_b32_e32 v62, 0xffff0000, v162
	s_waitcnt vmcnt(9)
	v_lshlrev_b32_e32 v162, 16, v178
	s_waitcnt vmcnt(8)
	v_lshlrev_b32_e32 v174, 16, v180
	v_and_b32_e32 v177, 0xffff0000, v180
	v_and_b32_e32 v209, 0xffff0000, v178
	v_lshlrev_b32_e32 v163, 16, v179
	v_lshlrev_b32_e32 v175, 16, v181
	v_and_b32_e32 v178, 0xffff0000, v181
	s_waitcnt vmcnt(7)
	v_lshlrev_b32_e32 v180, 16, v188
	v_and_b32_e32 v181, 0xffff0000, v188
	s_waitcnt vmcnt(5)
	v_lshlrev_b32_e32 v210, 16, v192
	v_and_b32_e32 v211, 0xffff0000, v192
	v_lshlrev_b32_e32 v213, 16, v193
	v_and_b32_e32 v193, 0xffff0000, v193
	v_and_b32_e32 v192, 0xffff0000, v189
	v_pk_add_f32 v[42:43], v[42:43], v[46:47]
	v_pk_add_f32 v[46:47], v[136:137], v[140:141]
	v_pk_add_f32 v[124:125], v[124:125], v[126:127]
	v_pk_add_f32 v[126:127], v[158:159], v[160:161]
	v_and_b32_e32 v179, 0xffff0000, v179
	v_lshlrev_b32_e32 v212, 16, v189
	v_and_b32_e32 v188, 0xffff0000, v191
	v_lshlrev_b32_e32 v189, 16, v191
	v_and_b32_e32 v216, 0xffff0000, v190
	v_lshlrev_b32_e32 v217, 16, v190
	s_waitcnt vmcnt(4)
	v_and_b32_e32 v190, 0xffff0000, v194
	v_lshlrev_b32_e32 v191, 16, v194
	v_pk_add_f32 v[136:137], v[144:145], v[142:143]
	v_pk_add_f32 v[140:141], v[148:149], v[148:149] op_sel:[1,0] op_sel_hi:[0,1]
	v_pk_add_f32 v[142:143], v[150:151], v[200:201]
	v_mov_b32_e32 v144, v203
	v_pk_add_f32 v[148:149], v[154:155], v[154:155] op_sel:[1,0] op_sel_hi:[0,1]
	v_pk_add_f32 v[150:151], v[152:153], v[204:205]
	v_pk_add_f32 v[152:153], v[206:207], v[156:157]
	v_pk_add_f32 v[160:161], v[174:175], v[162:163]
	v_pk_add_f32 v[156:157], v[180:181], v[210:211]
	v_pk_add_f32 v[162:163], v[192:193], v[192:193] op_sel:[1,0] op_sel_hi:[0,1]
	v_mov_b32_e32 v146, v42
	v_mov_b32_e32 v198, v46
	v_mov_b32_e32 v176, v124
	v_mov_b32_e32 v208, v126
	v_and_b32_e32 v214, 0xffff0000, v195
	v_lshlrev_b32_e32 v215, 16, v195
	v_pk_add_f32 v[154:155], v[178:179], v[178:179] op_sel:[1,0] op_sel_hi:[0,1]
	v_pk_add_f32 v[178:179], v[216:217], v[190:191]
	v_pk_mov_b32 v[180:181], v[42:43], v[136:137] op_sel:[1,0]
	v_pk_add_f32 v[144:145], v[144:145], v[202:203]
	v_pk_add_f32 v[190:191], v[142:143], v[142:143] op_sel:[0,1] op_sel_hi:[1,0]
	v_mov_b32_e32 v192, v148
	v_mov_b32_e32 v194, v142
	v_pk_mov_b32 v[142:143], v[142:143], v[148:149] op_sel:[1,0]
	v_pk_mov_b32 v[148:149], v[124:125], v[160:161] op_sel:[1,0]
	v_pk_add_f32 v[202:203], v[156:157], v[156:157] op_sel:[0,1] op_sel_hi:[1,0]
	v_mov_b32_e32 v204, v162
	v_mov_b32_e32 v206, v156
	v_pk_mov_b32 v[162:163], v[156:157], v[162:163] op_sel:[1,0]
	v_pk_add_f32 v[146:147], v[146:147], v[198:199]
	v_pk_add_f32 v[156:157], v[176:177], v[208:209]
	v_mov_b32_e32 v158, v213
	v_pk_add_f32 v[174:175], v[188:189], v[214:215]
	v_mov_b32_e32 v188, v47
	v_mov_b32_e32 v189, v137
	v_mov_b32_e32 v117, v140
	v_mov_b32_e32 v200, v127
	v_mov_b32_e32 v201, v161
	v_pk_add_f32 v[176:177], v[180:181], v[146:147]
	v_pk_mov_b32 v[140:141], v[146:147], v[140:141] op_sel:[1,0]
	v_pk_add_f32 v[146:147], v[148:149], v[156:157]
	v_mov_b32_e32 v119, v154
	v_pk_add_f32 v[158:159], v[158:159], v[212:213]
	v_pk_mov_b32 v[180:181], v[156:157], v[154:155] op_sel:[1,0]
	v_pk_add_f32 v[154:155], v[188:189], v[176:177]
	v_pk_add_f32 v[146:147], v[200:201], v[146:147]
	v_mov_b32_e32 v145, v153
	v_mov_b32_e32 v191, v152
	v_mov_b32_e32 v159, v179
	v_mov_b32_e32 v203, v178
	v_pk_add_f32 v[116:117], v[154:155], v[116:117]
	v_pk_add_f32 v[118:119], v[146:147], v[118:119]
	v_mov_b32_e32 v193, v151
	v_mov_b32_e32 v205, v175
	v_mov_b32_e32 v195, v144
	v_pk_add_f32 v[144:145], v[144:145], v[190:191]
	v_pk_add_f32 v[148:149], v[158:159], v[202:203]
	v_pk_add_f32 v[116:117], v[116:117], v[116:117] op_sel:[0,1] op_sel_hi:[1,0]
	v_pk_add_f32 v[118:119], v[118:119], v[118:119] op_sel:[0,1] op_sel_hi:[1,0]
	v_pk_add_f32 v[144:145], v[192:193], v[144:145]
	v_pk_add_f32 v[148:149], v[204:205], v[148:149]
	v_mov_b32_e32 v117, v150
	v_mov_b32_e32 v119, v174
	v_pk_add_f32 v[116:117], v[116:117], v[144:145]
	v_pk_add_f32 v[118:119], v[118:119], v[148:149]
	v_add_f32_e32 v116, v116, v117
	v_add_f32_e32 v117, v118, v119
	ds_bpermute_b32 v118, v165, v116
	ds_bpermute_b32 v119, v165, v117
	v_mov_b32_e32 v207, v158
	s_waitcnt lgkmcnt(2)
	v_mfma_f32_16x16x32_bf16 v[34:37], v[34:37], v[2:5], v[38:41]
	s_waitcnt lgkmcnt(1)
	v_add_f32_e32 v116, v116, v118
	s_waitcnt lgkmcnt(0)
	v_add_f32_e32 v117, v117, v119
	ds_bpermute_b32 v118, v166, v116
	ds_bpermute_b32 v119, v166, v117
	s_waitcnt vmcnt(1)
	v_and_b32_e32 v41, 0xffff0000, v105
	v_and_b32_e32 v40, 0xffff0000, v104
	v_mov_b32_e32 v38, v34
	s_waitcnt lgkmcnt(1)
	v_add_f32_e32 v116, v116, v118
	s_waitcnt lgkmcnt(0)
; DI unsigned pk2(float lo, float hi) { return f2bf(lo) | (f2bf(hi) << 16); }
; DI void rwkv_post_tile(int j, int item, LAS unsigned char* lds) {
;     ...
;             const float mean = sum * (1.f / 64.f); float vs = 0.f;
; #pragma unroll
;             for (int q = 0; q < 4; ++q)
; #pragma unroll
;                 for (int e = 0; e < 4; ++e) { y[q][e] -= mean; vs += y[q][e] * y[q][e]; }
;             vs += __shfl_xor(vs, 16); vs += __shfl_xor(vs, 32);
;             const float rstd = rsqrtf(vs * (1.f / 64.f) + 64e-5f);
;             const float sb = SB0[m * 16 + H] + SB1[m * 16 + H];
; #pragma unroll
;             for (int q = 0; q < 4; ++q) { const int c = nc * 128 + (hh * 4 + q) * 16 + fq * 4;
;                 const u32x2 vu = *(const u32x2*)(Vb + m * D + c); const float vf[4] = {bflo(vu.x), bfhi(vu.x), bflo(vu.y), bfhi(vu.y)};
;                 float o[4];
; #pragma unroll
;                 for (int e = 0; e < 4; ++e) o[e] = (y[q][e] * rstd * lng[c + e] + lnb[c + e] + sb * vf[e]) * acc[hh * 4 + q][e];
;                 u32x2 w; w.x = pk2(o[0], o[1]); w.y = pk2(o[2], o[3]);
;                 *(u32x2*)(Yo + m * D + c) = w; }
	v_add_f32_e32 v117, v117, v119
	v_mul_f32_e32 v116, 0x3c800000, v116
	v_mul_f32_e32 v118, 0x3c800000, v117
	v_pk_add_f32 v[176:177], v[150:151], v[116:117] op_sel_hi:[1,0] neg_lo:[0,1] neg_hi:[0,1]
	v_pk_add_f32 v[150:151], v[46:47], v[116:117] op_sel_hi:[1,0] neg_lo:[0,1] neg_hi:[0,1]
	v_pk_add_f32 v[144:145], v[126:127], v[118:119] op_sel_hi:[1,0] neg_lo:[0,1] neg_hi:[0,1]
	v_pk_add_f32 v[146:147], v[152:153], v[116:117] op_sel_hi:[1,0] neg_lo:[0,1] neg_hi:[0,1]
	v_pk_add_f32 v[148:149], v[42:43], v[116:117] op_sel_hi:[1,0] neg_lo:[0,1] neg_hi:[0,1]
	v_pk_add_f32 v[152:153], v[136:137], v[116:117] op_sel_hi:[1,0] neg_lo:[0,1] neg_hi:[0,1]
	v_pk_add_f32 v[42:43], v[178:179], v[118:119] op_sel_hi:[1,0] neg_lo:[0,1] neg_hi:[0,1]
	v_pk_add_f32 v[46:47], v[174:175], v[118:119] op_sel_hi:[1,0] neg_lo:[0,1] neg_hi:[0,1]
	v_pk_add_f32 v[136:137], v[124:125], v[118:119] op_sel_hi:[1,0] neg_lo:[0,1] neg_hi:[0,1]
	v_mov_b32_e32 v192, v144
	v_mov_b32_e32 v193, v150
	v_pk_add_f32 v[154:155], v[140:141], v[116:117] op_sel_hi:[1,0] neg_lo:[0,1] neg_hi:[0,1]
	v_pk_add_f32 v[158:159], v[142:143], v[116:117] op_sel_hi:[1,0] neg_lo:[0,1] neg_hi:[0,1]
	v_pk_add_f32 v[124:125], v[160:161], v[118:119] op_sel_hi:[1,0] neg_lo:[0,1] neg_hi:[0,1]
	v_pk_mul_f32 v[140:141], v[146:147], v[146:147]
	v_pk_mul_f32 v[142:143], v[176:177], v[176:177]
	v_mov_b32_e32 v160, v147
	v_mov_b32_e32 v161, v177
	v_mov_b32_e32 v147, v176
	v_pk_mul_f32 v[176:177], v[42:43], v[42:43]
	v_pk_mul_f32 v[178:179], v[46:47], v[46:47]
	v_mov_b32_e32 v190, v136
	v_mov_b32_e32 v191, v148
	v_pk_mul_f32 v[192:193], v[192:193], v[192:193]
	v_pk_add_f32 v[156:157], v[194:195], v[116:117] op_sel_hi:[1,0] neg_lo:[0,1] neg_hi:[0,1]
	v_mov_b32_e32 v194, v137
	v_mov_b32_e32 v195, v149
	v_mov_b32_e32 v208, v177
	v_mov_b32_e32 v209, v141
	v_mov_b32_e32 v177, v140
	v_mov_b32_e32 v140, v179
	v_mov_b32_e32 v141, v143
	v_mov_b32_e32 v179, v142
	v_pk_fma_f32 v[142:143], v[190:191], v[190:191], v[192:193]
	v_mov_b32_e32 v198, v145
	v_mov_b32_e32 v199, v151
	v_pk_fma_f32 v[142:143], v[194:195], v[194:195], v[142:143]
	v_pk_add_f32 v[126:127], v[180:181], v[118:119] op_sel_hi:[1,0] neg_lo:[0,1] neg_hi:[0,1]
	v_mov_b32_e32 v200, v124
	v_mov_b32_e32 v201, v152
	v_pk_fma_f32 v[142:143], v[198:199], v[198:199], v[142:143]
	v_pk_add_f32 v[116:117], v[206:207], v[118:119] op_sel_hi:[1,0] neg_lo:[0,1] neg_hi:[0,1]
	v_pk_add_f32 v[118:119], v[162:163], v[118:119] op_sel_hi:[1,0] neg_lo:[0,1] neg_hi:[0,1]
	v_mov_b32_e32 v202, v126
	v_mov_b32_e32 v203, v154
	v_pk_fma_f32 v[142:143], v[200:201], v[200:201], v[142:143]
	v_mov_b32_e32 v162, v158
	v_mov_b32_e32 v163, v156
	v_mov_b32_e32 v180, v118
	v_mov_b32_e32 v181, v116
	v_mov_b32_e32 v204, v125
	v_mov_b32_e32 v205, v153
	v_pk_fma_f32 v[142:143], v[202:203], v[202:203], v[142:143]
	v_mov_b32_e32 v206, v127
	v_mov_b32_e32 v207, v155
	v_pk_mul_f32 v[162:163], v[162:163], v[162:163]
	v_pk_mul_f32 v[180:181], v[180:181], v[180:181]
	v_pk_fma_f32 v[142:143], v[204:205], v[204:205], v[142:143]
	v_mov_b32_e32 v174, v159
	v_mov_b32_e32 v175, v157
	v_mov_b32_e32 v188, v119
	v_mov_b32_e32 v189, v117
	v_mov_b32_e32 v190, v181
	v_mov_b32_e32 v191, v163
	v_pk_fma_f32 v[142:143], v[206:207], v[206:207], v[142:143]
	v_pk_mul_f32 v[174:175], v[174:175], v[174:175]
	v_pk_mul_f32 v[188:189], v[188:189], v[188:189]
	v_mov_b32_e32 v181, v162
	v_pk_add_f32 v[142:143], v[190:191], v[142:143]
	v_mov_b32_e32 v162, v189
	v_mov_b32_e32 v163, v175
	v_pk_add_f32 v[142:143], v[180:181], v[142:143]
	v_mov_b32_e32 v189, v174
	v_pk_add_f32 v[142:143], v[162:163], v[142:143]
	v_mov_b32_e32 v39, v36
	v_pk_add_f32 v[142:143], v[188:189], v[142:143]
	v_mov_b32_e32 v36, v35
	v_pk_add_f32 v[142:143], v[208:209], v[142:143]
	v_lshlrev_b32_e32 v35, 16, v105
	v_pk_add_f32 v[142:143], v[176:177], v[142:143]
	v_lshlrev_b32_e32 v34, 16, v104
	v_pk_add_f32 v[140:141], v[140:141], v[142:143]
	v_mfma_f32_16x16x32_bf16 v[26:29], v[26:29], v[2:5], v[30:33]
	v_add_f32_e64 v140, v178, v140
	v_add_f32_e64 v141, v179, v141
	ds_bpermute_b32 v143, v165, v141
	ds_bpermute_b32 v142, v165, v140
	v_and_b32_e32 v33, 0xffff0000, v99
	v_and_b32_e32 v32, 0xffff0000, v98
	s_nop 1
	v_mov_b32_e32 v30, v26
	v_mov_b32_e32 v31, v28
	s_waitcnt lgkmcnt(0)
	v_pk_add_f32 v[140:141], v[140:141], v[142:143]
	ds_bpermute_b32 v143, v166, v141
	ds_bpermute_b32 v142, v166, v140
	v_mov_b32_e32 v28, v27
	v_lshlrev_b32_e32 v27, 16, v99
	v_lshlrev_b32_e32 v26, 16, v98
	s_waitcnt lgkmcnt(0)
	v_pk_add_f32 v[162:163], v[140:141], v[142:143]
	s_nop 0
	v_pk_fma_f32 v[140:141], v[162:163], s[4:5], v[164:165] op_sel_hi:[1,0,0]
	s_nop 0
	v_mul_f32_e32 v142, 0x4b800000, v141
	v_cmp_gt_f32_e64 s[4:5], s3, v141
	v_mul_f32_e32 v162, 0x4b800000, v140
	v_cmp_gt_f32_e32 vcc, s3, v140
	v_cndmask_b32_e64 v141, v141, v142, s[4:5]
	v_rsq_f32_e32 v141, v141
	s_nop 0
	v_mul_f32_e32 v142, 0x45800000, v141
	v_cndmask_b32_e64 v142, v141, v142, s[4:5]
	v_pk_mul_f32 v[150:151], v[150:151], v[142:143] op_sel_hi:[1,0]
	v_pk_mul_f32 v[148:149], v[148:149], v[142:143] op_sel_hi:[1,0]
	v_pk_fma_f32 v[60:61], v[60:61], v[150:151], v[64:65]
	v_pk_fma_f32 v[132:133], v[132:133], v[148:149], v[134:135]
	v_pk_fma_f32 v[60:61], v[0:1], v[130:131], v[60:61] op_sel_hi:[0,1,1]
	v_pk_fma_f32 v[64:65], v[0:1], v[128:129], v[132:133] op_sel_hi:[0,1,1]
	v_pk_mul_f32 v[60:61], v[68:69], v[60:61]
	v_pk_mul_f32 v[64:65], v[110:111], v[64:65]
	v_and_b32_sdwa v110, v61, v186 dst_sel:DWORD dst_unused:UNUSED_PAD src0_sel:WORD_1 src1_sel:DWORD
	v_and_b32_sdwa v111, v60, v186 dst_sel:DWORD dst_unused:UNUSED_PAD src0_sel:WORD_1 src1_sel:DWORD
	v_and_b32_sdwa v68, v65, v186 dst_sel:DWORD dst_unused:UNUSED_PAD src0_sel:WORD_1 src1_sel:DWORD
	v_and_b32_sdwa v69, v64, v186 dst_sel:DWORD dst_unused:UNUSED_PAD src0_sel:WORD_1 src1_sel:DWORD
	v_add3_u32 v61, v61, v110, s31
	v_add3_u32 v60, v60, v111, s31
	v_add3_u32 v64, v64, v69, s31
	v_add3_u32 v65, v65, v68, s31
	v_and_b32_e32 v61, 0xffff0000, v61
	v_and_b32_e32 v60, 0xffff0000, v60
	v_or_b32_sdwa v61, v61, v65 dst_sel:DWORD dst_unused:UNUSED_PAD src0_sel:DWORD src1_sel:WORD_1
	v_or_b32_sdwa v60, v60, v64 dst_sel:DWORD dst_unused:UNUSED_PAD src0_sel:DWORD src1_sel:WORD_1
	global_load_dwordx4 v[244:247], v[94:95], off offset:64
	global_load_dwordx4 v[248:251], v[96:97], off offset:64
	global_store_dwordx2 v[90:91], v[60:61], off
	v_pk_mul_f32 v[152:153], v[152:153], v[142:143] op_sel_hi:[1,0]
	v_pk_mul_f32 v[154:155], v[154:155], v[142:143] op_sel_hi:[1,0]
	v_pk_mul_f32 v[156:157], v[156:157], v[142:143] op_sel_hi:[1,0]
	v_pk_mul_f32 v[158:159], v[158:159], v[142:143] op_sel_hi:[1,0]
	v_pk_mul_f32 v[160:161], v[160:161], v[142:143] op_sel_hi:[1,0]
	v_pk_mul_f32 v[142:143], v[146:147], v[142:143] op_sel_hi:[1,0]
	s_waitcnt vmcnt(2)
; DI unsigned pk2(float lo, float hi) { return f2bf(lo) | (f2bf(hi) << 16); }
; DI void rwkv_post_tile(int j, int item, LAS unsigned char* lds) {
;     ...
;             const float sb = SB0[m * 16 + H] + SB1[m * 16 + H];
;     ...
;             for (int q = 0; q < 4; ++q) { const int c = nc * 128 + (hh * 4 + q) * 16 + fq * 4;
;                 const u32x2 vu = *(const u32x2*)(Vb + m * D + c); const float vf[4] = {bflo(vu.x), bfhi(vu.x), bflo(vu.y), bfhi(vu.y)};
;                 float o[4];
; #pragma unroll
;                 for (int e = 0; e < 4; ++e) o[e] = (y[q][e] * rstd * lng[c + e] + lnb[c + e] + sb * vf[e]) * acc[hh * 4 + q][e];
;                 u32x2 w; w.x = pk2(o[0], o[1]); w.y = pk2(o[2], o[3]);
;                 *(u32x2*)(Yo + m * D + c) = w; }
	v_mov_b64_e32 v[128:129], v[244:245]
	v_mov_b64_e32 v[130:131], v[246:247]
	v_mov_b32_e32 v60, v128
	v_mov_b32_e32 v61, v130
	s_waitcnt vmcnt(1)
	v_mov_b64_e32 v[132:133], v[248:249]
	v_mov_b64_e32 v[134:135], v[250:251]
	v_mov_b32_e32 v64, v132
	v_mov_b32_e32 v65, v134
	v_mov_b32_e32 v130, v129
	v_mov_b32_e32 v134, v133
	v_pk_fma_f32 v[60:61], v[60:61], v[152:153], v[64:65]
	v_pk_fma_f32 v[64:65], v[130:131], v[154:155], v[134:135]
	v_pk_fma_f32 v[60:61], v[0:1], v[120:121], v[60:61] op_sel_hi:[0,1,1]
	v_pk_fma_f32 v[64:65], v[0:1], v[122:123], v[64:65] op_sel_hi:[0,1,1]
	v_pk_mul_f32 v[56:57], v[56:57], v[64:65]
	v_pk_mul_f32 v[60:61], v[108:109], v[60:61]
	v_and_b32_sdwa v68, v57, v186 dst_sel:DWORD dst_unused:UNUSED_PAD src0_sel:WORD_1 src1_sel:DWORD
	v_and_b32_sdwa v69, v56, v186 dst_sel:DWORD dst_unused:UNUSED_PAD src0_sel:WORD_1 src1_sel:DWORD
	v_and_b32_sdwa v64, v61, v186 dst_sel:DWORD dst_unused:UNUSED_PAD src0_sel:WORD_1 src1_sel:DWORD
	v_and_b32_sdwa v65, v60, v186 dst_sel:DWORD dst_unused:UNUSED_PAD src0_sel:WORD_1 src1_sel:DWORD
	v_add3_u32 v57, v57, v68, s31
	v_add3_u32 v56, v56, v69, s31
	v_add3_u32 v60, v60, v65, s31
	v_add3_u32 v61, v61, v64, s31
	v_and_b32_e32 v57, 0xffff0000, v57
	v_and_b32_e32 v56, 0xffff0000, v56
	v_or_b32_sdwa v57, v57, v61 dst_sel:DWORD dst_unused:UNUSED_PAD src0_sel:DWORD src1_sel:WORD_1
	v_or_b32_sdwa v56, v56, v60 dst_sel:DWORD dst_unused:UNUSED_PAD src0_sel:DWORD src1_sel:WORD_1
	global_load_dwordx4 v[244:247], v[94:95], off offset:128
	global_load_dwordx4 v[248:251], v[96:97], off offset:128
	global_store_dwordx2 v[90:91], v[56:57], off offset:32
	s_waitcnt vmcnt(2)
	v_mov_b64_e32 v[108:109], v[244:245]
	v_mov_b64_e32 v[110:111], v[246:247]
	v_mov_b32_e32 v56, v108
	v_mov_b32_e32 v57, v110
	s_waitcnt vmcnt(1)
	v_mov_b64_e32 v[120:121], v[248:249]
	v_mov_b64_e32 v[122:123], v[250:251]
	v_mov_b32_e32 v60, v120
	v_mov_b32_e32 v61, v122
	v_mov_b32_e32 v110, v109
	v_mov_b32_e32 v122, v121
	v_pk_fma_f32 v[56:57], v[56:57], v[156:157], v[60:61]
	v_pk_fma_f32 v[60:61], v[110:111], v[158:159], v[122:123]
	v_pk_fma_f32 v[56:57], v[0:1], v[112:113], v[56:57] op_sel_hi:[0,1,1]
	v_pk_fma_f32 v[60:61], v[0:1], v[114:115], v[60:61] op_sel_hi:[0,1,1]
	v_pk_mul_f32 v[52:53], v[52:53], v[60:61]
	v_pk_mul_f32 v[56:57], v[66:67], v[56:57]
	v_and_b32_sdwa v64, v53, v186 dst_sel:DWORD dst_unused:UNUSED_PAD src0_sel:WORD_1 src1_sel:DWORD
	v_and_b32_sdwa v65, v52, v186 dst_sel:DWORD dst_unused:UNUSED_PAD src0_sel:WORD_1 src1_sel:DWORD
	v_and_b32_sdwa v60, v57, v186 dst_sel:DWORD dst_unused:UNUSED_PAD src0_sel:WORD_1 src1_sel:DWORD
	v_and_b32_sdwa v61, v56, v186 dst_sel:DWORD dst_unused:UNUSED_PAD src0_sel:WORD_1 src1_sel:DWORD
	v_add3_u32 v53, v53, v64, s31
	v_add3_u32 v52, v52, v65, s31
	v_add3_u32 v56, v56, v61, s31
	v_add3_u32 v57, v57, v60, s31
	v_and_b32_e32 v53, 0xffff0000, v53
	v_and_b32_e32 v52, 0xffff0000, v52
	v_or_b32_sdwa v53, v53, v57 dst_sel:DWORD dst_unused:UNUSED_PAD src0_sel:DWORD src1_sel:WORD_1
	v_or_b32_sdwa v52, v52, v56 dst_sel:DWORD dst_unused:UNUSED_PAD src0_sel:DWORD src1_sel:WORD_1
	global_load_dwordx4 v[244:247], v[94:95], off offset:192
	global_load_dwordx4 v[248:251], v[96:97], off offset:192
	global_store_dwordx2 v[90:91], v[52:53], off offset:64
	s_waitcnt vmcnt(2)
	v_mov_b64_e32 v[64:65], v[244:245]
	v_mov_b64_e32 v[66:67], v[246:247]
	v_mov_b32_e32 v52, v64
	v_mov_b32_e32 v53, v66
	s_waitcnt vmcnt(1)
	v_mov_b64_e32 v[108:109], v[248:249]
	v_mov_b64_e32 v[110:111], v[250:251]
	v_mov_b32_e32 v56, v108
	v_mov_b32_e32 v57, v110
	v_mov_b32_e32 v66, v65
	v_mov_b32_e32 v110, v109
	v_pk_fma_f32 v[52:53], v[52:53], v[160:161], v[56:57]
	v_pk_fma_f32 v[56:57], v[142:143], v[66:67], v[110:111]
	v_pk_fma_f32 v[52:53], v[0:1], v[58:59], v[52:53] op_sel_hi:[0,1,1]
	v_pk_fma_f32 v[56:57], v[0:1], v[62:63], v[56:57] op_sel_hi:[0,1,1]
	v_pk_mul_f32 v[48:49], v[48:49], v[56:57]
	v_pk_mul_f32 v[52:53], v[54:55], v[52:53]
	v_and_b32_sdwa v55, v49, v186 dst_sel:DWORD dst_unused:UNUSED_PAD src0_sel:WORD_1 src1_sel:DWORD
	v_and_b32_sdwa v56, v48, v186 dst_sel:DWORD dst_unused:UNUSED_PAD src0_sel:WORD_1 src1_sel:DWORD
	v_and_b32_sdwa v0, v53, v186 dst_sel:DWORD dst_unused:UNUSED_PAD src0_sel:WORD_1 src1_sel:DWORD
	v_and_b32_sdwa v54, v52, v186 dst_sel:DWORD dst_unused:UNUSED_PAD src0_sel:WORD_1 src1_sel:DWORD
	v_add3_u32 v49, v49, v55, s31
	v_add3_u32 v48, v48, v56, s31
	v_add3_u32 v52, v52, v54, s31
	v_add3_u32 v0, v53, v0, s31
	v_and_b32_e32 v49, 0xffff0000, v49
	v_and_b32_e32 v48, 0xffff0000, v48
	v_or_b32_sdwa v49, v49, v0 dst_sel:DWORD dst_unused:UNUSED_PAD src0_sel:DWORD src1_sel:WORD_1
	v_or_b32_sdwa v48, v48, v52 dst_sel:DWORD dst_unused:UNUSED_PAD src0_sel:DWORD src1_sel:WORD_1
	global_load_dwordx4 v[244:247], v[94:95], off offset:256
	global_load_dwordx4 v[248:251], v[96:97], off offset:256
	global_load_dword v236, v[100:101], off offset:4
	global_load_dword v237, v[102:103], off offset:4
	global_store_dwordx2 v[90:91], v[48:49], off offset:96
	v_cndmask_b32_e32 v48, v140, v162, vcc
	v_rsq_f32_e32 v48, v48
	v_and_b32_e32 v67, 0xffff0000, v107
	v_and_b32_e32 v66, 0xffff0000, v106
	v_lshlrev_b32_e32 v65, 16, v107
	v_mul_f32_e32 v60, 0x45800000, v48
	v_cndmask_b32_e32 v48, v48, v60, vcc
	v_lshlrev_b32_e32 v64, 16, v106
	s_waitcnt vmcnt(4)
	v_mov_b64_e32 v[52:53], v[244:245]
	v_mov_b64_e32 v[54:55], v[246:247]
	v_mov_b32_e32 v69, v54
	s_waitcnt vmcnt(3)
	v_mov_b64_e32 v[56:57], v[248:249]
	v_mov_b64_e32 v[58:59], v[250:251]
	v_mov_b32_e32 v101, v58
	v_mov_b32_e32 v54, v53
	s_waitcnt vmcnt(1)
; DI unsigned pk2(float lo, float hi) { return f2bf(lo) | (f2bf(hi) << 16); }
; DI void rwkv_post_tile(int j, int item, LAS unsigned char* lds) {
;     ...
;             const float sb = SB0[m * 16 + H] + SB1[m * 16 + H];
; #pragma unroll
;             for (int q = 0; q < 4; ++q) { const int c = nc * 128 + (hh * 4 + q) * 16 + fq * 4;
;                 const u32x2 vu = *(const u32x2*)(Vb + m * D + c); const float vf[4] = {bflo(vu.x), bfhi(vu.x), bflo(vu.y), bfhi(vu.y)};
;                 float o[4];
; #pragma unroll
;                 for (int e = 0; e < 4; ++e) o[e] = (y[q][e] * rstd * lng[c + e] + lnb[c + e] + sb * vf[e]) * acc[hh * 4 + q][e];
;                 u32x2 w; w.x = pk2(o[0], o[1]); w.y = pk2(o[2], o[3]);
;                 *(u32x2*)(Yo + m * D + c) = w; }
	v_mov_b32_e32 v0, v236
	v_mov_b32_e32 v49, v237
	v_pk_mul_f32 v[62:63], v[144:145], v[48:49] op_sel_hi:[1,0]
	v_mov_b32_e32 v58, v57
	v_pk_mul_f32 v[60:61], v[136:137], v[48:49] op_sel_hi:[1,0]
	v_add_f32_e32 v0, v0, v49
	v_mov_b32_e32 v68, v52
	v_mov_b32_e32 v100, v56
	v_pk_fma_f32 v[54:55], v[54:55], v[62:63], v[58:59]
	v_pk_fma_f32 v[52:53], v[68:69], v[60:61], v[100:101]
	v_pk_fma_f32 v[54:55], v[0:1], v[66:67], v[54:55] op_sel_hi:[0,1,1]
	v_pk_fma_f32 v[52:53], v[0:1], v[64:65], v[52:53] op_sel_hi:[0,1,1]
	v_pk_mul_f32 v[44:45], v[44:45], v[54:55]
	v_pk_mul_f32 v[50:51], v[50:51], v[52:53]
	v_and_b32_sdwa v53, v45, v186 dst_sel:DWORD dst_unused:UNUSED_PAD src0_sel:WORD_1 src1_sel:DWORD
	v_and_b32_sdwa v54, v44, v186 dst_sel:DWORD dst_unused:UNUSED_PAD src0_sel:WORD_1 src1_sel:DWORD
	v_and_b32_sdwa v49, v51, v186 dst_sel:DWORD dst_unused:UNUSED_PAD src0_sel:WORD_1 src1_sel:DWORD
	v_and_b32_sdwa v52, v50, v186 dst_sel:DWORD dst_unused:UNUSED_PAD src0_sel:WORD_1 src1_sel:DWORD
	v_add3_u32 v45, v45, v53, s31
	v_add3_u32 v44, v44, v54, s31
	v_add3_u32 v50, v50, v52, s31
	v_add3_u32 v49, v51, v49, s31
	v_and_b32_e32 v45, 0xffff0000, v45
	v_and_b32_e32 v44, 0xffff0000, v44
	v_or_b32_sdwa v45, v45, v49 dst_sel:DWORD dst_unused:UNUSED_PAD src0_sel:DWORD src1_sel:WORD_1
	v_or_b32_sdwa v44, v44, v50 dst_sel:DWORD dst_unused:UNUSED_PAD src0_sel:DWORD src1_sel:WORD_1
	global_load_dwordx4 v[244:247], v[94:95], off offset:320
	global_load_dwordx4 v[248:251], v[96:97], off offset:320
	global_store_dwordx2 v[90:91], v[44:45], off offset:128
	v_pk_mul_f32 v[58:59], v[126:127], v[48:49] op_sel_hi:[1,0]
	v_pk_mul_f32 v[44:45], v[124:125], v[48:49] op_sel_hi:[1,0]
	s_waitcnt vmcnt(2)
	v_mov_b64_e32 v[50:51], v[244:245]
	v_mov_b64_e32 v[52:53], v[246:247]
	v_mov_b32_e32 v61, v52
	s_waitcnt vmcnt(1)
	v_mov_b64_e32 v[54:55], v[248:249]
	v_mov_b64_e32 v[56:57], v[250:251]
	v_mov_b32_e32 v63, v56
	v_mov_b32_e32 v52, v51
	v_mov_b32_e32 v56, v55
	v_mov_b32_e32 v60, v50
	v_mov_b32_e32 v62, v54
	v_pk_fma_f32 v[50:51], v[52:53], v[58:59], v[56:57]
	v_pk_fma_f32 v[44:45], v[60:61], v[44:45], v[62:63]
	v_pk_fma_f32 v[40:41], v[0:1], v[40:41], v[50:51] op_sel_hi:[0,1,1]
	v_pk_fma_f32 v[34:35], v[0:1], v[34:35], v[44:45] op_sel_hi:[0,1,1]
	v_pk_mul_f32 v[36:37], v[36:37], v[40:41]
	v_pk_mul_f32 v[34:35], v[38:39], v[34:35]
	v_and_b32_sdwa v40, v37, v186 dst_sel:DWORD dst_unused:UNUSED_PAD src0_sel:WORD_1 src1_sel:DWORD
	v_and_b32_sdwa v41, v36, v186 dst_sel:DWORD dst_unused:UNUSED_PAD src0_sel:WORD_1 src1_sel:DWORD
	v_and_b32_sdwa v38, v35, v186 dst_sel:DWORD dst_unused:UNUSED_PAD src0_sel:WORD_1 src1_sel:DWORD
	v_and_b32_sdwa v39, v34, v186 dst_sel:DWORD dst_unused:UNUSED_PAD src0_sel:WORD_1 src1_sel:DWORD
	v_add3_u32 v37, v37, v40, s31
	v_add3_u32 v36, v36, v41, s31
	v_add3_u32 v34, v34, v39, s31
	v_add3_u32 v35, v35, v38, s31
	v_and_b32_e32 v37, 0xffff0000, v37
	v_and_b32_e32 v36, 0xffff0000, v36
	v_or_b32_sdwa v35, v37, v35 dst_sel:DWORD dst_unused:UNUSED_PAD src0_sel:DWORD src1_sel:WORD_1
	v_or_b32_sdwa v34, v36, v34 dst_sel:DWORD dst_unused:UNUSED_PAD src0_sel:DWORD src1_sel:WORD_1
	global_load_dwordx4 v[244:247], v[94:95], off offset:384
	global_load_dwordx4 v[248:251], v[96:97], off offset:384
	global_store_dwordx2 v[90:91], v[34:35], off offset:160
	v_pk_mul_f32 v[50:51], v[118:119], v[48:49] op_sel_hi:[1,0]
	v_pk_mul_f32 v[44:45], v[116:117], v[48:49] op_sel_hi:[1,0]
	s_waitcnt vmcnt(2)
	v_mov_b64_e32 v[34:35], v[244:245]
	v_mov_b64_e32 v[36:37], v[246:247]
	v_mov_b32_e32 v53, v36
	s_waitcnt vmcnt(1)
; DI unsigned pk2(float lo, float hi) { return f2bf(lo) | (f2bf(hi) << 16); }
; DI void rwkv_post_tile(int j, int item, LAS unsigned char* lds) {
;     ...
;         mm16<8, 6>(As + wave * 16 * 200, 200, Bs, 200, acc, fr, fq);
;     ...
;             for (int q = 0; q < 4; ++q) { const int c = nc * 128 + (hh * 4 + q) * 16 + fq * 4;
;                 const u32x2 vu = *(const u32x2*)(Vb + m * D + c); const float vf[4] = {bflo(vu.x), bfhi(vu.x), bflo(vu.y), bfhi(vu.y)};
;                 float o[4];
; #pragma unroll
;                 for (int e = 0; e < 4; ++e) o[e] = (y[q][e] * rstd * lng[c + e] + lnb[c + e] + sb * vf[e]) * acc[hh * 4 + q][e];
;                 u32x2 w; w.x = pk2(o[0], o[1]); w.y = pk2(o[2], o[3]);
;                 *(u32x2*)(Yo + m * D + c) = w; }
;         }
;     }
	v_mov_b64_e32 v[38:39], v[248:249]
	v_mov_b64_e32 v[40:41], v[250:251]
	v_mov_b32_e32 v55, v40
	v_mov_b32_e32 v36, v35
	v_mov_b32_e32 v40, v39
	v_mov_b32_e32 v52, v34
	v_mov_b32_e32 v54, v38
	v_pk_fma_f32 v[36:37], v[36:37], v[50:51], v[40:41]
	v_pk_fma_f32 v[34:35], v[52:53], v[44:45], v[54:55]
	v_pk_fma_f32 v[32:33], v[0:1], v[32:33], v[36:37] op_sel_hi:[0,1,1]
	v_pk_fma_f32 v[26:27], v[0:1], v[26:27], v[34:35] op_sel_hi:[0,1,1]
	v_pk_mul_f32 v[28:29], v[28:29], v[32:33]
	v_pk_mul_f32 v[26:27], v[30:31], v[26:27]
	v_and_b32_sdwa v32, v29, v186 dst_sel:DWORD dst_unused:UNUSED_PAD src0_sel:WORD_1 src1_sel:DWORD
	v_and_b32_sdwa v33, v28, v186 dst_sel:DWORD dst_unused:UNUSED_PAD src0_sel:WORD_1 src1_sel:DWORD
	v_and_b32_sdwa v30, v27, v186 dst_sel:DWORD dst_unused:UNUSED_PAD src0_sel:WORD_1 src1_sel:DWORD
	v_and_b32_sdwa v31, v26, v186 dst_sel:DWORD dst_unused:UNUSED_PAD src0_sel:WORD_1 src1_sel:DWORD
	v_add3_u32 v29, v29, v32, s31
	v_add3_u32 v28, v28, v33, s31
	v_add3_u32 v26, v26, v31, s31
	v_add3_u32 v27, v27, v30, s31
	v_and_b32_e32 v29, 0xffff0000, v29
	v_and_b32_e32 v28, 0xffff0000, v28
	v_or_b32_sdwa v27, v29, v27 dst_sel:DWORD dst_unused:UNUSED_PAD src0_sel:DWORD src1_sel:WORD_1
	v_or_b32_sdwa v26, v28, v26 dst_sel:DWORD dst_unused:UNUSED_PAD src0_sel:DWORD src1_sel:WORD_1
	global_load_dwordx4 v[244:247], v[94:95], off offset:448
	global_load_dwordx4 v[248:251], v[96:97], off offset:448
	global_store_dwordx2 v[90:91], v[26:27], off offset:192
	ds_read_b128 v[34:37], v173 offset:44800
	ds_read_b128 v[38:41], v173 offset:44864
	s_waitcnt lgkmcnt(1)
	v_mfma_f32_16x16x32_bf16 v[10:13], v[34:37], v[10:13], 0
	ds_read_b128 v[34:37], v173 offset:44928
	s_waitcnt lgkmcnt(1)
	v_mfma_f32_16x16x32_bf16 v[6:9], v[38:41], v[6:9], v[10:13]
	s_nop 4
	ds_read_b128 v[10:13], v173 offset:44992
	s_waitcnt lgkmcnt(1)
	v_mfma_f32_16x16x32_bf16 v[6:9], v[34:37], v[18:21], v[6:9]
	ds_read_b128 v[18:21], v173 offset:45056
	s_waitcnt lgkmcnt(1)
	v_mfma_f32_16x16x32_bf16 v[10:13], v[10:13], v[14:17], v[6:9]
	s_nop 4
	ds_read_b128 v[6:9], v173 offset:45120
	s_waitcnt vmcnt(2)
	v_mov_b64_e32 v[26:27], v[244:245]
	v_mov_b64_e32 v[28:29], v[246:247]
	v_mov_b32_e32 v14, v26
	s_waitcnt lgkmcnt(1)
	v_mfma_f32_16x16x32_bf16 v[10:13], v[18:21], v[22:25], v[10:13]
	v_mov_b32_e32 v15, v28
	s_waitcnt vmcnt(1)
	v_mov_b64_e32 v[30:31], v[248:249]
	v_mov_b64_e32 v[32:33], v[250:251]
	v_mov_b32_e32 v16, v30
	v_mov_b32_e32 v17, v32
	s_waitcnt lgkmcnt(0)
	v_mfma_f32_16x16x32_bf16 v[2:5], v[6:9], v[2:5], v[10:13]
	v_mov_b32_e32 v28, v27
	v_mov_b32_e32 v32, v31
	v_and_b32_e32 v9, 0xffff0000, v93
	v_mov_b32_e32 v10, v43
	v_mov_b32_e32 v11, v47
	v_mov_b32_e32 v43, v46
	v_pk_mul_f32 v[10:11], v[10:11], v[48:49] op_sel_hi:[1,0]
	v_pk_mul_f32 v[12:13], v[42:43], v[48:49] op_sel_hi:[1,0]
	v_mov_b32_e32 v6, v2
	v_mov_b32_e32 v7, v4
	v_mov_b32_e32 v4, v3
	v_lshlrev_b32_e32 v3, 16, v93
	v_lshlrev_b32_e32 v2, 16, v92
	v_and_b32_e32 v8, 0xffff0000, v92
	v_pk_fma_f32 v[10:11], v[14:15], v[10:11], v[16:17]
	v_pk_fma_f32 v[12:13], v[12:13], v[28:29], v[32:33]
	v_pk_fma_f32 v[2:3], v[0:1], v[2:3], v[10:11] op_sel_hi:[0,1,1]
	v_pk_fma_f32 v[8:9], v[0:1], v[8:9], v[12:13] op_sel_hi:[0,1,1]
	v_pk_mul_f32 v[2:3], v[6:7], v[2:3]
	v_pk_mul_f32 v[4:5], v[4:5], v[8:9]
	v_and_b32_sdwa v0, v3, v186 dst_sel:DWORD dst_unused:UNUSED_PAD src0_sel:WORD_1 src1_sel:DWORD
	v_and_b32_sdwa v7, v5, v186 dst_sel:DWORD dst_unused:UNUSED_PAD src0_sel:WORD_1 src1_sel:DWORD
	v_and_b32_sdwa v8, v4, v186 dst_sel:DWORD dst_unused:UNUSED_PAD src0_sel:WORD_1 src1_sel:DWORD
	v_and_b32_sdwa v6, v2, v186 dst_sel:DWORD dst_unused:UNUSED_PAD src0_sel:WORD_1 src1_sel:DWORD
	v_add3_u32 v0, v3, v0, s31
	v_add3_u32 v3, v5, v7, s31
	v_add3_u32 v4, v4, v8, s31
	v_add3_u32 v2, v2, v6, s31
	v_and_b32_e32 v3, 0xffff0000, v3
	v_and_b32_e32 v4, 0xffff0000, v4
	v_or_b32_sdwa v3, v3, v0 dst_sel:DWORD dst_unused:UNUSED_PAD src0_sel:DWORD src1_sel:WORD_1
	v_or_b32_sdwa v2, v4, v2 dst_sel:DWORD dst_unused:UNUSED_PAD src0_sel:DWORD src1_sel:WORD_1
	global_store_dwordx2 v[90:91], v[2:3], off offset:224
	s_cbranch_scc1 .LBB0_100
	s_barrier
	s_branch .LBB0_95

; #define LAS __attribute__((address_space(3)))
; DI const float* modp(const unsigned char* ws, int layer, int who, int idx) { return (const float*)(ws + WS_MOD) + ((size_t)(layer * 9 + who) * 6 + idx) * D; }
; DI void phase_rw_mix(int layer, int j, int q, LAS unsigned char* lds) {
;     ...
;             const int t = t0 - 1 + rr;
;             if (t < 0 || t >= T) {
; #pragma unroll
;                 for (int jj = 0; jj < 4; ++jj) *(LAS f32x4*)(hs + rr * 1024 + 4 * lane + 256 * jj) = (f32x4){0.f, 0.f, 0.f, 0.f};
;             } else {
;                 const int who = t < LC ? 8 : b; const float* sh = modp(ws, layer, who, 0); const float* sc = modp(ws, layer, who, 1);
;                 const float* z = zrow(ws, outp, b * T + t); f32x4 v[4]; float ss = 0.f;
; #pragma unroll
;                 for (int jj = 0; jj < 4; ++jj) { v[jj] = *(const f32x4*)(z + 4 * lane + 256 * jj); ss += v[jj][0] * v[jj][0] + v[jj][1] * v[jj][1] + v[jj][2] * v[jj][2] + v[jj][3] * v[jj][3]; }
;                 const float rstd = rsqrtf(wave_sum(ss) * (1.f / D) + 1e-6f);
.LBB0_455:
	v_add3_u32 v5, s22, v21, 7
	s_movk_i32 s2, 0x1100
	v_cmp_gt_u32_e32 vcc, s2, v5
	s_and_saveexec_b64 s[2:3], vcc
	s_xor_b64 s[18:19], exec, s[2:3]
	s_cbranch_execz .LBB0_461
	v_add_u32_e32 v8, s23, v21
	v_add_u32_e32 v2, 7, v8
	s_mov_b32 s2, 0x78787879
	v_mul_hi_i32 v3, v2, s2
	v_lshrrev_b32_e32 v4, 31, v3
	v_ashrrev_i32_e32 v3, 11, v3
	v_add_u32_e32 v6, v3, v4
	s_movk_i32 s2, 0xef00
	v_mad_i32_i24 v2, v6, s2, v2
	s_movk_i32 s2, 0xff
	v_mul_i32_i24_e32 v7, 0xffffef00, v6
	v_cmp_lt_i32_e32 vcc, s2, v2
	v_mov_b64_e32 v[2:3], s[6:7]
	s_and_saveexec_b64 s[2:3], vcc
	s_xor_b64 s[2:3], exec, s[2:3]
	v_lshl_add_u32 v2, v6, 12, v7
	s_movk_i32 s28, 0xff07
	v_add3_u32 v4, v8, v2, s28
	v_mov_b64_e32 v[2:3], s[10:11]
	s_andn2_saveexec_b64 s[2:3], s[2:3]
	v_add_u32_e32 v4, s25, v25
	v_lshlrev_b32_e32 v6, 8, v6
	v_add3_u32 v4, v7, v4, v6
	s_or_b64 exec, exec, s[2:3]
	s_movk_i32 s2, 0xff
	v_cmp_lt_u32_e32 vcc, s2, v5
	v_mov_b32_e32 v5, s24
	v_readlane_b32 s2, v255, 31
	v_cndmask_b32_e32 v5, 8, v5, vcc
	s_mul_i32 s2, s2, 9
	v_add_u32_e32 v5, s2, v5
	v_mul_i32_i24_e32 v6, 6, v5
	v_ashrrev_i32_e32 v5, 31, v4
	v_lshlrev_b64 v[4:5], 12, v[4:5]
	v_lshl_add_u64 v[2:3], v[2:3], 0, v[4:5]
	v_lshl_add_u64 v[2:3], v[2:3], 0, v[0:1]
	global_load_dwordx4 v[26:29], v[2:3], off
	global_load_dwordx4 v[10:13], v[2:3], off offset:1024
	global_load_dwordx4 v[108:111], v[2:3], off offset:2048
	global_load_dwordx4 v[112:115], v[2:3], off offset:3072
	v_ashrrev_i32_e32 v7, 31, v6
	v_lshlrev_b64 v[6:7], 12, v[6:7]
	v_lshl_add_u64 v[14:15], s[12:13], 0, v[6:7]
	v_xor_b32_e32 v20, 1, v187
	s_mov_b64 s[2:3], 0x1000
	v_lshl_add_u64 v[18:19], v[14:15], 0, s[2:3]
	s_mov_b32 s2, 0x800000
	v_mov_b32_e32 v79, v1
	v_mov_b32_e32 v81, v1
	v_mov_b32_e32 v83, v1
	s_waitcnt vmcnt(3)
	v_mov_b32_e32 v6, v27
	s_waitcnt vmcnt(2)
	v_mov_b32_e32 v7, v11
	v_mov_b32_e32 v4, v26
	v_mov_b32_e32 v5, v10
	v_pk_mul_f32 v[6:7], v[6:7], v[6:7]
	s_nop 0
	v_pk_fma_f32 v[4:5], v[4:5], v[4:5], v[6:7]
	v_mov_b32_e32 v6, v28
	v_mov_b32_e32 v7, v12
	v_pk_fma_f32 v[4:5], v[6:7], v[6:7], v[4:5]
	v_mov_b32_e32 v6, v29
	v_mov_b32_e32 v7, v13
	v_pk_fma_f32 v[16:17], v[6:7], v[6:7], v[4:5]
	s_waitcnt vmcnt(0)
	v_mov_b64_e32 v[6:7], v[108:109]
	v_mov_b64_e32 v[8:9], v[110:111]
	v_mov_b64_e32 v[4:5], v[114:115]
	v_mov_b64_e32 v[2:3], v[112:113]
	v_add_f32_e32 v16, v16, v17
	v_and_b32_e32 v17, 64, v187
	v_add_u32_e32 v17, 64, v17
	v_cmp_lt_i32_e32 vcc, v20, v17
	s_waitcnt vmcnt(1)
	v_mov_b32_e32 v30, v7
	s_waitcnt vmcnt(0)
	v_mov_b32_e32 v31, v3
	v_mov_b32_e32 v22, v6
	v_mov_b32_e32 v23, v2
	v_pk_mul_f32 v[30:31], v[30:31], v[30:31]
	v_cndmask_b32_e32 v20, v187, v20, vcc
	v_pk_fma_f32 v[22:23], v[22:23], v[22:23], v[30:31]
	v_mov_b32_e32 v30, v8
	v_mov_b32_e32 v31, v4
	v_pk_fma_f32 v[22:23], v[30:31], v[30:31], v[22:23]
	v_mov_b32_e32 v30, v9
	v_mov_b32_e32 v31, v5
	v_pk_fma_f32 v[22:23], v[30:31], v[30:31], v[22:23]
	v_lshlrev_b32_e32 v20, 2, v20
	v_add_f32_e32 v16, v16, v22
	v_add_f32_e32 v16, v16, v23
	ds_bpermute_b32 v20, v20, v16
	global_load_dwordx4 v[30:33], v[52:53], off
	v_lshl_add_u64 v[22:23], v[14:15], 0, v[0:1]
	s_waitcnt lgkmcnt(0)
	v_add_f32_e32 v16, v16, v20
	v_xor_b32_e32 v20, 2, v187
	v_cmp_lt_i32_e32 vcc, v20, v17
	s_nop 1
	v_cndmask_b32_e32 v20, v187, v20, vcc
	v_lshlrev_b32_e32 v20, 2, v20
	ds_bpermute_b32 v20, v20, v16
	s_waitcnt lgkmcnt(0)
	v_add_f32_e32 v16, v16, v20
	v_xor_b32_e32 v20, 4, v187
	v_cmp_lt_i32_e32 vcc, v20, v17
	s_nop 1
	v_cndmask_b32_e32 v20, v187, v20, vcc
	v_lshlrev_b32_e32 v20, 2, v20
	ds_bpermute_b32 v20, v20, v16
	s_waitcnt lgkmcnt(0)
	v_add_f32_e32 v16, v16, v20
	v_xor_b32_e32 v20, 8, v187
	v_cmp_lt_i32_e32 vcc, v20, v17
	s_nop 1
	v_cndmask_b32_e32 v20, v187, v20, vcc
	v_lshlrev_b32_e32 v20, 2, v20
	ds_bpermute_b32 v20, v20, v16
	s_waitcnt lgkmcnt(0)
	v_add_f32_e32 v16, v16, v20
	v_xor_b32_e32 v20, 16, v187
	v_cmp_lt_i32_e32 vcc, v20, v17
	s_nop 1
	v_cndmask_b32_e32 v20, v187, v20, vcc
	v_lshlrev_b32_e32 v20, 2, v20
	ds_bpermute_b32 v20, v20, v16
	s_waitcnt lgkmcnt(0)
; #define LAS __attribute__((address_space(3)))
; DI void phase_rw_mix(int layer, int j, int q, LAS unsigned char* lds) {
;     ...
;                 const float rstd = rsqrtf(wave_sum(ss) * (1.f / D) + 1e-6f);
; #pragma unroll
;                 for (int jj = 0; jj < 4; ++jj) { const int c = 4 * lane + 256 * jj;
;                     const f32x4 gg = *(const f32x4*)(g + c), a1 = *(const f32x4*)(sc + c), a0 = *(const f32x4*)(sh + c);
;                     f32x4 y = v[jj] * rstd * gg; y = y * (a1 + 1.f) + a0; *(LAS f32x4*)(hs + rr * 1024 + c) = y; }
	v_add_f32_e32 v16, v16, v20
	v_xor_b32_e32 v20, 32, v187
	v_cmp_lt_i32_e32 vcc, v20, v17
	s_nop 1
	v_cndmask_b32_e32 v17, v187, v20, vcc
	v_lshlrev_b32_e32 v17, 2, v17
	ds_bpermute_b32 v17, v17, v16
	s_waitcnt lgkmcnt(0)
	v_add_f32_e32 v16, v16, v17
	v_fmamk_f32 v16, v16, 0x3a800000, v183
	v_cmp_gt_f32_e32 vcc, s2, v16
	v_mul_f32_e32 v17, 0x4b800000, v16
	s_nop 0
	v_cndmask_b32_e32 v16, v16, v17, vcc
	v_rsq_f32_e32 v16, v16
	s_nop 0
	v_mul_f32_e32 v17, 0x45800000, v16
	v_cndmask_b32_e32 v20, v16, v17, vcc
	v_lshl_add_u64 v[16:17], v[18:19], 0, v[0:1]
	global_load_dwordx4 v[34:37], v[16:17], off
	v_pk_mul_f32 v[28:29], v[28:29], v[20:21] op_sel_hi:[1,0]
	global_load_dwordx4 v[14:17], v[22:23], off
	global_load_dwordx4 v[116:119], v[52:53], off offset:1024
	v_lshl_add_u64 v[152:153], v[18:19], 0, v[78:79]
	global_load_dwordx4 v[120:123], v[152:153], off
	global_load_dwordx4 v[124:127], v[22:23], off offset:1024
	global_load_dwordx4 v[128:131], v[52:53], off offset:2048
	v_lshl_add_u64 v[154:155], v[18:19], 0, v[80:81]
	global_load_dwordx4 v[132:135], v[154:155], off
	global_load_dwordx4 v[140:143], v[22:23], off offset:2048
	global_load_dwordx4 v[144:147], v[52:53], off offset:3072
	v_lshl_add_u64 v[156:157], v[18:19], 0, v[82:83]
	global_load_dwordx4 v[148:151], v[156:157], off
	global_load_dwordx4 v[158:161], v[22:23], off offset:3072
	v_pk_mul_f32 v[26:27], v[26:27], v[20:21] op_sel_hi:[1,0]
	s_waitcnt vmcnt(11)
	v_pk_mul_f32 v[28:29], v[32:33], v[28:29]
	v_pk_mul_f32 v[26:27], v[30:31], v[26:27]
	v_pk_mul_f32 v[12:13], v[12:13], v[20:21] op_sel_hi:[1,0]
	v_pk_mul_f32 v[10:11], v[10:11], v[20:21] op_sel_hi:[1,0]
	v_pk_mul_f32 v[8:9], v[8:9], v[20:21] op_sel_hi:[1,0]
	v_pk_mul_f32 v[6:7], v[6:7], v[20:21] op_sel_hi:[1,0]
	v_pk_mul_f32 v[4:5], v[4:5], v[20:21] op_sel_hi:[1,0]
	v_pk_mul_f32 v[2:3], v[2:3], v[20:21] op_sel_hi:[1,0]
	s_waitcnt vmcnt(10)
	v_pk_add_f32 v[30:31], v[36:37], 1.0 op_sel_hi:[1,0]
	v_pk_add_f32 v[32:33], v[34:35], 1.0 op_sel_hi:[1,0]
	s_waitcnt vmcnt(9)
	v_pk_fma_f32 v[16:17], v[30:31], v[28:29], v[16:17]
	v_pk_fma_f32 v[14:15], v[32:33], v[26:27], v[14:15]
	ds_write_b128 v24, v[14:17]
	s_waitcnt vmcnt(6)
	v_mov_b64_e32 v[14:15], v[116:117]
	v_mov_b64_e32 v[16:17], v[118:119]
	v_lshl_add_u64 v[26:27], v[18:19], 0, v[78:79]
	v_mov_b64_e32 v[26:27], v[120:121]
	v_mov_b64_e32 v[28:29], v[122:123]
	s_nop 0
	v_mov_b64_e32 v[30:31], v[124:125]
	v_mov_b64_e32 v[32:33], v[126:127]
	v_pk_mul_f32 v[10:11], v[14:15], v[10:11]
	v_pk_mul_f32 v[12:13], v[16:17], v[12:13]
	v_pk_add_f32 v[14:15], v[28:29], 1.0 op_sel_hi:[1,0]
	v_pk_add_f32 v[16:17], v[26:27], 1.0 op_sel_hi:[1,0]
	v_pk_fma_f32 v[12:13], v[14:15], v[12:13], v[32:33]
	v_pk_fma_f32 v[10:11], v[16:17], v[10:11], v[30:31]
	ds_write_b128 v24, v[10:13] offset:1024
	s_waitcnt vmcnt(3)
	v_mov_b64_e32 v[10:11], v[128:129]
	v_mov_b64_e32 v[12:13], v[130:131]
	v_lshl_add_u64 v[14:15], v[18:19], 0, v[80:81]
	v_mov_b64_e32 v[14:15], v[132:133]
	v_mov_b64_e32 v[16:17], v[134:135]
	s_nop 0
	v_mov_b64_e32 v[26:27], v[140:141]
	v_mov_b64_e32 v[28:29], v[142:143]
	v_pk_mul_f32 v[6:7], v[10:11], v[6:7]
	v_pk_mul_f32 v[8:9], v[12:13], v[8:9]
	v_pk_add_f32 v[10:11], v[16:17], 1.0 op_sel_hi:[1,0]
	v_pk_add_f32 v[12:13], v[14:15], 1.0 op_sel_hi:[1,0]
	v_pk_fma_f32 v[8:9], v[10:11], v[8:9], v[28:29]
	v_pk_fma_f32 v[6:7], v[12:13], v[6:7], v[26:27]
	ds_write_b128 v24, v[6:9] offset:2048
	s_waitcnt vmcnt(0)
	v_mov_b64_e32 v[14:15], v[144:145]
	v_mov_b64_e32 v[16:17], v[146:147]
	v_lshl_add_u64 v[6:7], v[18:19], 0, v[82:83]
	v_mov_b64_e32 v[6:7], v[148:149]
	v_mov_b64_e32 v[8:9], v[150:151]
	s_nop 0
	v_mov_b64_e32 v[10:11], v[158:159]
	v_mov_b64_e32 v[12:13], v[160:161]
	v_pk_mul_f32 v[2:3], v[14:15], v[2:3]
	v_pk_mul_f32 v[4:5], v[16:17], v[4:5]
	v_pk_add_f32 v[8:9], v[8:9], 1.0 op_sel_hi:[1,0]
	v_pk_add_f32 v[6:7], v[6:7], 1.0 op_sel_hi:[1,0]
	v_pk_fma_f32 v[4:5], v[4:5], v[8:9], v[12:13]
	v_pk_fma_f32 v[2:3], v[2:3], v[6:7], v[10:11]
	ds_write_b128 v24, v[2:5] offset:3072
